# scan: one bf16 matvec per 2 tokens (second token's sa/yp corrected with cross-token dots computed by the prep waves), rank-4 update on 16x16x4 f32 MFMA
# speedup vs baseline: 1.0435x; 1.0177x over previous
.LBB0_787:
	global_load_dwordx4 v[108:111], v[114:115], off
	s_add_i32 s34, s6, 2
	s_cmp_ge_u32 s34, s43
	s_cbranch_scc1 .LBB0_784
	s_bitcmp1_b32 s34, 0
	s_cselect_b32 s34, 0xe180, 0
	s_add_i32 s34, s34, 16
	v_lshlrev_b32_e32 v136, 2, v118
	v_add3_u32 v142, s34, v136, v149
	s_waitcnt vmcnt(8)
	v_lshlrev_b32_e32 v136, 16, v72
	v_and_b32_e32 v137, 0xffff0000, v72
	v_lshlrev_b32_e32 v138, 16, v68
	v_and_b32_e32 v139, 0xffff0000, v68
	v_pk_add_f32 v[136:137], v[136:137], v[138:139] neg_lo:[0,1] neg_hi:[0,1]
	v_lshlrev_b32_e32 v140, 16, v69
	v_pk_fma_f32 v[136:137], v[4:5], v[136:137], v[138:139]
	v_lshlrev_b32_e32 v138, 16, v73
	v_and_b32_e32 v139, 0xffff0000, v73
	v_and_b32_e32 v141, 0xffff0000, v69
	v_pk_add_f32 v[138:139], v[138:139], v[140:141] neg_lo:[0,1] neg_hi:[0,1]
	s_waitcnt vmcnt(2)
	v_lshlrev_b32_e32 v145, 16, v96
	v_pk_fma_f32 v[138:139], v[6:7], v[138:139], v[140:141]
	ds_write_b128 v142, v[136:139] offset:32768
	v_lshlrev_b32_e32 v136, 16, v74
	v_and_b32_e32 v137, 0xffff0000, v74
	v_lshlrev_b32_e32 v138, 16, v70
	v_and_b32_e32 v139, 0xffff0000, v70
	v_pk_add_f32 v[136:137], v[136:137], v[138:139] neg_lo:[0,1] neg_hi:[0,1]
	v_lshlrev_b32_e32 v140, 16, v71
	v_pk_fma_f32 v[136:137], v[8:9], v[136:137], v[138:139]
	v_lshlrev_b32_e32 v138, 16, v75
	v_and_b32_e32 v139, 0xffff0000, v75
	v_and_b32_e32 v141, 0xffff0000, v71
	v_pk_add_f32 v[138:139], v[138:139], v[140:141] neg_lo:[0,1] neg_hi:[0,1]
	v_lshlrev_b32_e32 v143, 16, v94
	v_pk_fma_f32 v[138:139], v[10:11], v[138:139], v[140:141]
	ds_write_b128 v142, v[136:139] offset:32784
	v_lshlrev_b32_e32 v136, 16, v80
	v_and_b32_e32 v137, 0xffff0000, v80
	v_lshlrev_b32_e32 v138, 16, v76
	v_and_b32_e32 v139, 0xffff0000, v76
	v_pk_add_f32 v[136:137], v[136:137], v[138:139] neg_lo:[0,1] neg_hi:[0,1]
	v_lshlrev_b32_e32 v140, 16, v77
	v_pk_fma_f32 v[136:137], v[44:45], v[136:137], v[138:139]
	v_lshlrev_b32_e32 v138, 16, v81
	v_and_b32_e32 v139, 0xffff0000, v81
	v_and_b32_e32 v141, 0xffff0000, v77
	v_pk_add_f32 v[138:139], v[138:139], v[140:141] neg_lo:[0,1] neg_hi:[0,1]
	v_lshlrev_b32_e32 v144, 16, v98
	v_pk_fma_f32 v[138:139], v[46:47], v[138:139], v[140:141]
	ds_write_b128 v142, v[136:139] offset:24576
	v_lshlrev_b32_e32 v136, 16, v82
	v_and_b32_e32 v137, 0xffff0000, v82
	v_lshlrev_b32_e32 v138, 16, v78
	v_and_b32_e32 v139, 0xffff0000, v78
	v_pk_add_f32 v[136:137], v[136:137], v[138:139] neg_lo:[0,1] neg_hi:[0,1]
	v_lshlrev_b32_e32 v140, 16, v79
	v_pk_fma_f32 v[136:137], v[48:49], v[136:137], v[138:139]
	v_lshlrev_b32_e32 v138, 16, v83
	v_and_b32_e32 v139, 0xffff0000, v83
	v_and_b32_e32 v141, 0xffff0000, v79
	v_pk_add_f32 v[138:139], v[138:139], v[140:141] neg_lo:[0,1] neg_hi:[0,1]
	v_sub_f32_e32 v144, v144, v143
	v_pk_fma_f32 v[138:139], v[50:51], v[138:139], v[140:141]
	ds_write_b128 v142, v[136:139] offset:24592
	v_lshlrev_b32_e32 v136, 16, v88
	v_and_b32_e32 v137, 0xffff0000, v88
	v_lshlrev_b32_e32 v138, 16, v84
	v_and_b32_e32 v139, 0xffff0000, v84
	v_pk_add_f32 v[136:137], v[136:137], v[138:139] neg_lo:[0,1] neg_hi:[0,1]
	v_lshlrev_b32_e32 v140, 16, v85
	v_pk_fma_f32 v[136:137], v[52:53], v[136:137], v[138:139]
	v_lshlrev_b32_e32 v138, 16, v89
	v_and_b32_e32 v139, 0xffff0000, v89
	v_and_b32_e32 v141, 0xffff0000, v85
	v_pk_add_f32 v[138:139], v[138:139], v[140:141] neg_lo:[0,1] neg_hi:[0,1]
	v_fmac_f32_e32 v143, v16, v144
	v_pk_fma_f32 v[138:139], v[54:55], v[138:139], v[140:141]
	ds_write_b128 v142, v[136:139] offset:40960
	v_lshlrev_b32_e32 v136, 16, v90
	v_and_b32_e32 v137, 0xffff0000, v90
	v_lshlrev_b32_e32 v138, 16, v86
	v_and_b32_e32 v139, 0xffff0000, v86
	v_pk_add_f32 v[136:137], v[136:137], v[138:139] neg_lo:[0,1] neg_hi:[0,1]
	v_lshlrev_b32_e32 v140, 16, v87
	v_pk_fma_f32 v[136:137], v[56:57], v[136:137], v[138:139]
	v_lshlrev_b32_e32 v138, 16, v91
	v_and_b32_e32 v139, 0xffff0000, v91
	v_and_b32_e32 v141, 0xffff0000, v87
	v_pk_add_f32 v[138:139], v[138:139], v[140:141] neg_lo:[0,1] neg_hi:[0,1]
	v_add3_u32 v214, s34, v155, v120
	v_pk_fma_f32 v[138:139], v[58:59], v[138:139], v[140:141]
	ds_write_b128 v142, v[136:139] offset:40976
	v_and_b32_e32 v140, 0xffff0000, v95
	v_and_b32_e32 v136, 0xffff0000, v99
	v_sub_f32_e32 v136, v136, v140
	v_fmac_f32_e32 v140, v19, v136
	v_lshlrev_b32_e32 v141, 16, v95
	v_lshlrev_b32_e32 v136, 16, v99
	v_sub_f32_e32 v136, v136, v141
	v_fmac_f32_e32 v141, v18, v136
	v_and_b32_e32 v142, 0xffff0000, v94
	v_and_b32_e32 v136, 0xffff0000, v98
	v_sub_f32_e32 v136, v136, v142
	v_fmac_f32_e32 v142, v17, v136
	v_and_b32_e32 v136, 0xffff0000, v93
	v_and_b32_e32 v137, 0xffff0000, v97
	v_sub_f32_e32 v137, v137, v136
	v_fmac_f32_e32 v136, v15, v137
	v_lshlrev_b32_e32 v137, 16, v93
	v_lshlrev_b32_e32 v138, 16, v97
	v_sub_f32_e32 v138, v138, v137
	v_fmac_f32_e32 v137, v14, v138
	v_and_b32_e32 v138, 0xffff0000, v92
	v_and_b32_e32 v139, 0xffff0000, v96
	v_sub_f32_e32 v139, v139, v138
	v_fmac_f32_e32 v138, v13, v139
	v_lshlrev_b32_e32 v139, 16, v92
	v_sub_f32_e32 v145, v145, v139
	v_fmac_f32_e32 v139, v12, v145
	v_add_f32_e32 v139, v139, v139
	v_add_f32_e32 v138, v138, v138
	v_mul_f32_e32 v139, 0x3fb8aa3b, v139
	v_mul_f32_e32 v138, 0x3fb8aa3b, v138
	v_add_f32_e32 v137, v137, v137
	v_add_f32_e32 v136, v136, v136
	v_exp_f32_e32 v139, v139
	v_exp_f32_e32 v138, v138
	v_mul_f32_e32 v137, 0x3fb8aa3b, v137
	v_mul_f32_e32 v136, 0x3fb8aa3b, v136
	v_exp_f32_e32 v137, v137
	v_exp_f32_e32 v136, v136
	v_add_f32_e32 v139, 1.0, v139
	v_add_f32_e32 v138, 1.0, v138
	v_add_f32_e32 v145, 1.0, v137
	v_add_f32_e32 v146, 1.0, v136
	v_rcp_f32_e64 v137, -v138
	v_rcp_f32_e64 v136, -v139
	v_rcp_f32_e64 v139, -v146
	v_add_f32_e32 v141, v141, v141
	v_add_f32_e32 v140, v140, v140
	v_pk_fma_f32 v[136:137], v[136:137], 2.0, 1.0 op_sel_hi:[1,0,0]
	v_mul_f32_e32 v141, 0x3fb8aa3b, v141
	v_bfe_u32 v146, v137, 16, 1
	v_bfe_u32 v147, v136, 16, 1
	v_add3_u32 v147, v136, v147, s89
	v_add3_u32 v146, v137, v146, s89
	v_add_f32_e32 v136, v143, v143
	v_add_f32_e32 v137, v142, v142
	v_mul_f32_e32 v136, 0x3fb8aa3b, v136
	v_mul_f32_e32 v137, 0x3fb8aa3b, v137
	v_mul_f32_e32 v140, 0x3fb8aa3b, v140
	v_exp_f32_e32 v136, v136
	v_exp_f32_e32 v137, v137
	v_exp_f32_e32 v141, v141
	v_exp_f32_e32 v140, v140
	v_rcp_f32_e64 v138, -v145
	v_add_f32_e32 v136, 1.0, v136
	v_add_f32_e32 v137, 1.0, v137
	v_add_f32_e32 v142, 1.0, v141
	v_add_f32_e32 v140, 1.0, v140
	v_rcp_f32_e64 v137, -v137
	v_rcp_f32_e64 v136, -v136
	v_rcp_f32_e64 v141, -v140
	v_rcp_f32_e64 v140, -v142
	v_pk_fma_f32 v[138:139], v[138:139], 2.0, 1.0 op_sel_hi:[1,0,0]
	v_pk_fma_f32 v[136:137], v[136:137], 2.0, 1.0 op_sel_hi:[1,0,0]
	v_bfe_u32 v144, v139, 16, 1
	v_bfe_u32 v145, v138, 16, 1
	v_add3_u32 v142, v138, v145, s89
	v_add3_u32 v143, v139, v144, s89
	v_pk_fma_f32 v[138:139], v[140:141], 2.0, 1.0 op_sel_hi:[1,0,0]
	v_bfe_u32 v144, v137, 16, 1
	v_bfe_u32 v140, v139, 16, 1
	v_bfe_u32 v141, v138, 16, 1
	v_bfe_u32 v145, v136, 16, 1
	v_add3_u32 v136, v136, v145, s89
	v_add3_u32 v137, v137, v144, s89
	v_add3_u32 v138, v138, v141, s89
	v_add3_u32 v139, v139, v140, s89
	v_perm_b32 v139, v139, v138, s90
	v_perm_b32 v138, v137, v136, s90
	v_perm_b32 v137, v143, v142, s90
	v_perm_b32 v136, v146, v147, s90
	ds_write_b128 v121, v[136:139]
	s_waitcnt vmcnt(1)
	v_lshlrev_b32_e32 v142, 16, v104
	v_lshlrev_b32_e32 v140, 16, v105
	v_and_b32_e32 v143, 0xffff0000, v104
	v_and_b32_e32 v141, 0xffff0000, v105
	v_lshlrev_b32_e32 v136, 16, v100
	v_lshlrev_b32_e32 v138, 16, v101
	v_and_b32_e32 v137, 0xffff0000, v100
	v_and_b32_e32 v139, 0xffff0000, v101
	v_sub_f32_e32 v141, v141, v139
	v_sub_f32_e32 v140, v140, v138
	v_sub_f32_e32 v143, v143, v137
	v_sub_f32_e32 v142, v142, v136
	v_pk_fma_f32 v[136:137], v[60:61], v[142:143], v[136:137]
	v_pk_fma_f32 v[138:139], v[62:63], v[140:141], v[138:139]
	v_bfe_u32 v142, v137, 16, 1
	v_bfe_u32 v140, v139, 16, 1
	v_bfe_u32 v141, v138, 16, 1
	v_bfe_u32 v143, v136, 16, 1
	v_add3_u32 v144, v136, v143, s89
	v_add3_u32 v145, v137, v142, s89
	v_add3_u32 v146, v138, v141, s89
	v_add3_u32 v147, v139, v140, s89
	v_lshlrev_b32_e32 v142, 16, v106
	v_lshlrev_b32_e32 v140, 16, v107
	v_and_b32_e32 v143, 0xffff0000, v106
	v_and_b32_e32 v141, 0xffff0000, v107
	v_lshlrev_b32_e32 v136, 16, v102
	v_lshlrev_b32_e32 v138, 16, v103
	v_and_b32_e32 v137, 0xffff0000, v102
	v_and_b32_e32 v139, 0xffff0000, v103
	v_sub_f32_e32 v141, v141, v139
	v_sub_f32_e32 v140, v140, v138
	v_sub_f32_e32 v143, v143, v137
	v_sub_f32_e32 v142, v142, v136
	v_pk_fma_f32 v[136:137], v[64:65], v[142:143], v[136:137]
	v_pk_fma_f32 v[138:139], v[66:67], v[140:141], v[138:139]
	v_bfe_u32 v142, v137, 16, 1
	v_bfe_u32 v140, v139, 16, 1
	v_bfe_u32 v141, v138, 16, 1
	v_bfe_u32 v143, v136, 16, 1
	v_add3_u32 v136, v136, v143, s89
	v_add3_u32 v137, v137, v142, s89
	v_add3_u32 v138, v138, v141, s89
	v_add3_u32 v139, v139, v140, s89
	v_perm_b32 v139, v139, v138, s90
	v_perm_b32 v138, v137, v136, s90
	v_perm_b32 v137, v147, v146, s90
	v_perm_b32 v136, v145, v144, s90
	ds_write_b128 v159, v[136:139]
	s_waitcnt lgkmcnt(0)
	ds_read_b128 v[136:139], v150
	ds_read_b128 v[140:143], v150 offset:64
	ds_read_b128 v[144:147], v160
	ds_read_b128 v[162:165], v160 offset:64
	s_waitcnt lgkmcnt(1)
	v_mfma_f32_16x16x32_bf16 v[144:147], v[136:139], v[144:147], 0
	v_lshl_add_u32 v215, v156, 2, s34
	v_lshl_add_u32 v216, v156, 3, s34
	s_waitcnt lgkmcnt(0)
	v_mfma_f32_16x16x32_bf16 v[144:147], v[140:143], v[162:165], v[144:147]
	ds_read_b128 v[162:165], v160 offset:2304
	ds_read_b128 v[166:169], v160 offset:2368
	s_waitcnt lgkmcnt(1)
	v_mfma_f32_16x16x32_bf16 v[162:165], v[136:139], v[162:165], 0
	s_waitcnt lgkmcnt(0)
	v_mfma_f32_16x16x32_bf16 v[162:165], v[140:143], v[166:169], v[162:165]
	ds_read_b128 v[166:169], v160 offset:4608
	ds_read_b128 v[170:173], v160 offset:4672
	s_waitcnt lgkmcnt(1)
	v_mfma_f32_16x16x32_bf16 v[166:169], v[136:139], v[166:169], 0
	s_waitcnt lgkmcnt(0)
	v_mfma_f32_16x16x32_bf16 v[166:169], v[140:143], v[170:173], v[166:169]
	ds_read_b128 v[170:173], v160 offset:6912
	ds_read_b128 v[174:177], v160 offset:6976
	s_waitcnt lgkmcnt(1)
	v_mfma_f32_16x16x32_bf16 v[136:139], v[136:139], v[170:173], 0
	ds_read_b128 v[170:173], v151
	s_nop 2
	v_cndmask_b32_e64 v144, v144, v166, s[0:1]
	v_add_f32_e32 v144, v124, v144
	s_waitcnt lgkmcnt(1)
	v_mfma_f32_16x16x32_bf16 v[136:139], v[140:143], v[174:177], v[136:139]
	ds_read_b128 v[140:143], v151 offset:64
	ds_read_b128 v[174:177], v160 offset:9216
	ds_read_b128 v[178:181], v160 offset:9280
	v_mul_f32_e32 v144, 0xbfb8aa3b, v144
	v_exp_f32_e32 v144, v144
	s_waitcnt lgkmcnt(1)
	v_mfma_f32_16x16x32_bf16 v[174:177], v[170:173], v[174:177], 0
	v_cndmask_b32_e64 v145, v145, v167, s[0:1]
	v_add_f32_e32 v144, 1.0, v144
	v_rcp_f32_e32 v144, v144
	s_waitcnt lgkmcnt(0)
	v_mfma_f32_16x16x32_bf16 v[174:177], v[140:143], v[178:181], v[174:177]
	ds_read_b128 v[178:181], v160 offset:11520
	ds_read_b128 v[184:187], v160 offset:11584
	v_add_f32_e32 v145, v124, v145
	v_mul_f32_e32 v144, 0xbf1b4598, v144
	s_waitcnt lgkmcnt(1)
	v_mfma_f32_16x16x32_bf16 v[178:181], v[170:173], v[178:181], 0
	v_mul_f32_e32 v144, 0x3fb8aa3b, v144
	v_mul_f32_e32 v145, 0xbfb8aa3b, v145
	v_exp_f32_e32 v144, v144
	s_waitcnt lgkmcnt(0)
	v_mfma_f32_16x16x32_bf16 v[178:181], v[140:143], v[184:187], v[178:181]
	ds_read_b128 v[184:187], v160 offset:13824
	ds_read_b128 v[188:191], v160 offset:13888
	v_exp_f32_e32 v145, v145
	v_cndmask_b32_e64 v147, v147, v169, s[0:1]
	s_waitcnt lgkmcnt(1)
	v_mfma_f32_16x16x32_bf16 v[184:187], v[170:173], v[184:187], 0
	v_cndmask_b32_e64 v146, v146, v168, s[0:1]
	v_lshl_add_u32 v169, v152, 2, s34
	v_cndmask_b32_e64 v136, v162, v136, s[0:1]
	s_waitcnt lgkmcnt(0)
	v_mfma_f32_16x16x32_bf16 v[184:187], v[140:143], v[188:191], v[184:187]
	ds_read_b128 v[188:191], v160 offset:16128
	ds_read_b128 v[192:195], v160 offset:16192
	v_add_f32_e32 v147, v124, v147
	v_add_f32_e32 v136, v125, v136
	s_waitcnt lgkmcnt(1)
	v_mfma_f32_16x16x32_bf16 v[170:173], v[170:173], v[188:191], 0
	s_nop 1
	v_cndmask_b32_e64 v167, v174, v184, s[0:1]
	v_add_f32_e32 v167, v126, v167
	v_mul_f32_e32 v167, 0xbfb8aa3b, v167
	v_exp_f32_e32 v167, v167
	v_mul_f32_e32 v147, 0xbfb8aa3b, v147
	v_mul_f32_e32 v136, 0xbfb8aa3b, v136
	s_waitcnt lgkmcnt(0)
	v_mfma_f32_16x16x32_bf16 v[140:143], v[140:143], v[192:195], v[170:173]
	v_add_f32_e32 v167, 1.0, v167
	v_rcp_f32_e32 v167, v167
	v_exp_f32_e32 v147, v147
	v_exp_f32_e32 v136, v136
	v_cndmask_b32_e64 v161, v177, v187, s[0:1]
	ds_write2st64_b32 v169, v144, v167 offset1:64
	v_mov_b32_e32 v252, v144
	v_add_f32_e32 v144, 1.0, v145
	v_add_f32_e32 v145, v124, v146
	v_mul_f32_e32 v145, 0xbfb8aa3b, v145
	v_exp_f32_e32 v145, v145
	v_cndmask_b32_e64 v166, v176, v186, s[0:1]
	v_cndmask_b32_e64 v168, v175, v185, s[0:1]
	v_add_f32_e32 v147, 1.0, v147
	v_add_f32_e32 v145, 1.0, v145
	v_cndmask_b32_e64 v137, v163, v137, s[0:1]
	v_add_f32_e32 v136, 1.0, v136
	v_cndmask_b32_e64 v140, v178, v140, s[0:1]
	v_rcp_f32_e32 v144, v144
	v_rcp_f32_e32 v145, v145
	v_add_f32_e32 v146, v126, v168
	v_add_f32_e32 v166, v126, v166
	v_rcp_f32_e32 v147, v147
	v_add_f32_e32 v161, v126, v161
	v_rcp_f32_e32 v136, v136
	v_add_f32_e32 v140, v127, v140
	v_add_f32_e32 v137, v125, v137
	v_mul_f32_e32 v146, 0xbfb8aa3b, v146
	v_mul_f32_e32 v166, 0xbfb8aa3b, v166
	v_mul_f32_e32 v161, 0xbfb8aa3b, v161
	v_mul_f32_e32 v140, 0xbfb8aa3b, v140
	v_mul_f32_e32 v137, 0xbfb8aa3b, v137
	v_exp_f32_e32 v146, v146
	v_exp_f32_e32 v166, v166
	v_exp_f32_e32 v161, v161
	v_exp_f32_e32 v140, v140
	v_exp_f32_e32 v137, v137
	v_mul_f32_e32 v144, 0xbf1b4598, v144
	v_mul_f32_e32 v145, 0xbf1b4598, v145
	v_mul_f32_e32 v147, 0xbf1b4598, v147
	v_mul_f32_e32 v136, 0xbf1b4598, v136
	v_mul_f32_e32 v144, 0x3fb8aa3b, v144
	v_mul_f32_e32 v145, 0x3fb8aa3b, v145
	v_mul_f32_e32 v147, 0x3fb8aa3b, v147
	v_mul_f32_e32 v136, 0x3fb8aa3b, v136
	v_exp_f32_e32 v144, v144
	v_exp_f32_e32 v145, v145
	v_add_f32_e32 v166, 1.0, v166
	v_exp_f32_e32 v147, v147
	v_add_f32_e32 v161, 1.0, v161
	v_add_f32_e32 v146, 1.0, v146
	v_exp_f32_e32 v136, v136
	v_add_f32_e32 v140, 1.0, v140
	v_add_f32_e32 v137, 1.0, v137
	v_rcp_f32_e32 v166, v166
	v_rcp_f32_e32 v161, v161
	v_rcp_f32_e32 v146, v146
	v_rcp_f32_e32 v140, v140
	v_rcp_f32_e32 v137, v137
	v_mul_f32_e32 v144, v144, v252
	v_mul_f32_e32 v145, v145, v144
	v_mul_f32_e32 v147, v147, v145
	v_mov_b32_e32 v253, v136
	ds_write2st64_b32 v169, v145, v147 offset0:2 offset1:3
	ds_write2st64_b32 v169, v166, v161 offset0:66 offset1:67
	v_cndmask_b32_e64 v138, v164, v138, s[0:1]
	ds_write2_b32 v169, v136, v144 offset0:16 offset1:64
	v_add_u32_e32 v136, 0x4000, v169
	v_cndmask_b32_e64 v139, v165, v139, s[0:1]
	ds_write2_b32 v136, v140, v146 offset0:16 offset1:64
	v_mul_f32_e32 v136, 0xbf1b4598, v137
	v_add_f32_e32 v137, v125, v138
	v_mul_f32_e32 v137, 0xbfb8aa3b, v137
	v_add_f32_e32 v139, v125, v139
	v_exp_f32_e32 v137, v137
	v_mul_f32_e32 v139, 0xbfb8aa3b, v139
	v_exp_f32_e32 v139, v139
	v_cndmask_b32_e64 v141, v179, v141, s[0:1]
	v_add_f32_e32 v137, 1.0, v137
	v_cndmask_b32_e64 v143, v181, v143, s[0:1]
	v_cndmask_b32_e64 v142, v180, v142, s[0:1]
	v_add_f32_e32 v138, v127, v141
	v_rcp_f32_e32 v137, v137
	v_add_f32_e32 v139, 1.0, v139
	v_mul_f32_e32 v138, 0xbfb8aa3b, v138
	v_add_f32_e32 v140, v127, v142
	v_rcp_f32_e32 v139, v139
	v_add_f32_e32 v141, v127, v143
	v_exp_f32_e32 v138, v138
	v_mul_f32_e32 v140, 0xbfb8aa3b, v140
	v_mul_f32_e32 v141, 0xbfb8aa3b, v141
	v_exp_f32_e32 v140, v140
	v_exp_f32_e32 v141, v141
	v_mul_f32_e32 v137, 0xbf1b4598, v137
	v_mul_f32_e32 v136, 0x3fb8aa3b, v136
	v_mul_f32_e32 v137, 0x3fb8aa3b, v137
	v_mul_f32_e32 v139, 0xbf1b4598, v139
	v_exp_f32_e32 v136, v136
	v_add_f32_e32 v138, 1.0, v138
	v_exp_f32_e32 v137, v137
	v_mul_f32_e32 v139, 0x3fb8aa3b, v139
	v_rcp_f32_e32 v138, v138
	v_add_f32_e32 v140, 1.0, v140
	v_exp_f32_e32 v139, v139
	v_add_f32_e32 v141, 1.0, v141
	v_rcp_f32_e32 v140, v140
	v_rcp_f32_e32 v141, v141
	v_lshl_add_u32 v142, v153, 2, s34
	v_mul_f32_e32 v136, v136, v253
	v_mul_f32_e32 v137, v137, v136
	v_mul_f32_e32 v139, v139, v137
	ds_write2st64_b32 v142, v136, v137 offset0:1 offset1:2
	ds_write2st64_b32 v142, v139, v138 offset0:3 offset1:65
	ds_write2st64_b32 v142, v140, v141 offset0:66 offset1:67
	s_waitcnt lgkmcnt(0)
	v_lshl_add_u32 v161, v154, 2, s34
	v_add_u32_e32 v254, 0xffffff00, v161
	ds_read_b128 v[228:231], v254
	ds_read_b128 v[232:235], v254 offset:16
	v_mbcnt_lo_u32_b32 v219, -1, 0
	v_mbcnt_hi_u32_b32 v219, -1, v219
	v_and_b32_e32 v217, 24, v219
	v_cmp_ne_u32_e64 s[44:45], 0, v217
	ds_read_b128 v[136:139], v161 offset:32768
	ds_read_b128 v[140:143], v161
	ds_read_b128 v[144:147], v161 offset:16
	ds_read_b128 v[162:165], v161 offset:32784
	s_add_i32 s34, s6, 3
	s_cmp_ge_u32 s34, s43
	s_waitcnt lgkmcnt(2)
	v_mul_f32_e32 v206, v136, v140
	v_mul_f32_e32 v207, v137, v141
	v_mul_f32_e32 v208, v138, v142
	v_mul_f32_e32 v209, v139, v143
	s_waitcnt lgkmcnt(0)
	v_mul_f32_e32 v210, v162, v144
	v_mul_f32_e32 v211, v163, v145
	v_mul_f32_e32 v212, v164, v146
	v_mul_f32_e32 v213, v165, v147
	v_rcp_f32_e32 v220, v140
	v_rcp_f32_e32 v221, v141
	v_rcp_f32_e32 v222, v142
	v_rcp_f32_e32 v223, v143
	v_rcp_f32_e32 v224, v144
	v_rcp_f32_e32 v225, v145
	v_rcp_f32_e32 v226, v146
	v_rcp_f32_e32 v227, v147
	v_cndmask_b32_e64 v228, 1.0, v228, s[44:45]
	v_cndmask_b32_e64 v229, 1.0, v229, s[44:45]
	v_cndmask_b32_e64 v230, 1.0, v230, s[44:45]
	v_cndmask_b32_e64 v231, 1.0, v231, s[44:45]
	v_cndmask_b32_e64 v232, 1.0, v232, s[44:45]
	v_cndmask_b32_e64 v233, 1.0, v233, s[44:45]
	v_cndmask_b32_e64 v234, 1.0, v234, s[44:45]
	v_cndmask_b32_e64 v235, 1.0, v235, s[44:45]
	ds_read_b128 v[140:143], v161 offset:16384
	ds_read_b128 v[144:147], v161 offset:16400
	ds_read_b128 v[166:169], v161 offset:24576
	ds_read_b128 v[170:173], v161 offset:24592
	s_waitcnt lgkmcnt(3)
	v_pk_add_f32 v[186:187], v[140:141], -1.0 op_sel_hi:[1,0]
	s_nop 0
	v_pk_fma_f32 v[186:187], v[28:29], v[186:187], 1.0 op_sel_hi:[1,1,0]
	s_waitcnt lgkmcnt(1)
	v_pk_mul_f32 v[184:185], v[20:21], v[166:167]
	v_pk_mul_f32 v[166:167], v[166:167], v[186:187]
	v_add_f32_e32 v187, -1.0, v142
	v_mov_b32_e32 v186, v168
	v_pk_mul_f32 v[198:199], v[22:23], v[186:187]
	v_add_f32_e32 v175, -1.0, v144
	s_waitcnt lgkmcnt(0)
	v_mov_b32_e32 v174, v170
	v_add_f32_e32 v191, -1.0, v143
	v_mov_b32_e32 v190, v169
	v_mov_b32_e32 v200, v184
	v_mov_b32_e32 v201, v198
	v_pk_mul_f32 v[176:177], v[24:25], v[174:175]
	v_pk_mul_f32 v[192:193], v[30:31], v[190:191]
	v_pk_mul_f32 v[200:201], v[200:201], v[200:201]
	v_mov_b32_e32 v188, v142
	v_mov_b32_e32 v194, v192
	v_mov_b32_e32 v195, v176
	v_fma_f32 v142, v185, v185, v200
	v_pk_mul_f32 v[194:195], v[194:195], v[194:195]
	v_add_f32_e32 v142, v142, v201
	v_add_f32_e32 v203, -1.0, v145
	v_mov_b32_e32 v202, v171
	v_add_f32_e32 v142, v142, v194
	v_pk_mul_f32 v[178:179], v[26:27], v[172:173]
	v_pk_mul_f32 v[204:205], v[32:33], v[202:203]
	v_add_f32_e32 v142, v142, v195
	v_pk_mul_f32 v[180:181], v[178:179], v[178:179]
	v_fmac_f32_e32 v142, v204, v204
	v_add_f32_e32 v142, v142, v180
	v_add_f32_e32 v142, v142, v181
	v_mov_b32_e32 v189, v168
	v_mov_b32_e32 v168, v143
	v_add_f32_dpp v142, v142, v142 quad_perm:[1,0,3,2] row_mask:0xf bank_mask:0xf bound_ctrl:1
	v_mov_b32_e32 v194, v144
	v_mul_f32_e32 v144, v137, v167
	v_add_f32_dpp v142, v142, v142 quad_perm:[2,3,0,1] row_mask:0xf bank_mask:0xf bound_ctrl:1
	v_mov_b32_e32 v180, v139
	v_mov_b32_e32 v195, v170
	v_add_f32_dpp v142, v142, v142 row_half_mirror row_mask:0xf bank_mask:0xf bound_ctrl:1
	v_max_f32_e32 v142, 0x179abe15, v142
	v_rsq_f32_e32 v182, v142
	v_mov_b32_e32 v170, v145
	v_mov_b32_e32 v145, v172
	v_mov_b32_e32 v172, v147
	v_pk_mul_f32 v[142:143], v[184:185], v[182:183] op_sel_hi:[1,0]
	v_mov_b32_e32 v185, v166
	v_pk_mul_f32 v[140:141], v[140:141], v[142:143]
	v_xor_b32_e32 v181, 0x80000000, v142
	v_mov_b32_e32 v184, v140
	v_mul_f32_e32 v142, v136, v166
	v_fma_f32 v200, v36, v142, 0
	v_pk_fma_f32 v[184:185], v[136:137], v[184:185], 0 op_sel_hi:[0,1,0]
	v_xor_b32_e32 v201, 0x80000000, v143
	v_mov_b32_e32 v142, v141
	v_mov_b32_e32 v143, v167
	v_pk_fma_f32 v[136:137], v[136:137], v[142:143], v[184:185] op_sel:[1,0,0]
	v_pk_mul_f32 v[142:143], v[198:199], v[182:183]
	v_pk_fma_f32 v[184:185], v[22:23], v[186:187], s[2:3]
	v_fmac_f32_e32 v200, v37, v144
	v_mov_b32_e32 v143, v185
	v_pk_mul_f32 v[184:185], v[188:189], v[142:143]
	v_xor_b32_e32 v188, 0x80000000, v142
	v_mul_f32_e32 v142, v185, v138
	v_fmac_f32_e32 v200, v38, v142
	v_pk_mul_f32 v[142:143], v[192:193], v[182:183]
	v_pk_fma_f32 v[186:187], v[30:31], v[190:191], s[2:3]
	v_pk_fma_f32 v[136:137], v[184:185], v[138:139], v[136:137] op_sel_hi:[1,0,1]
	v_mov_b32_e32 v143, v187
	v_pk_mul_f32 v[186:187], v[168:169], v[142:143]
	v_xor_b32_e32 v189, 0x80000000, v142
	v_mov_b32_e32 v142, v184
	v_mov_b32_e32 v143, v186
	v_mul_f32_e32 v138, v187, v139
	v_pk_mul_f32 v[236:237], v[140:141], v[220:221]
	v_pk_mul_f32 v[238:239], v[142:143], v[222:223]
	ds_write_b128 v161, v[236:239] offset:16384
	v_fmac_f32_e32 v200, v39, v138
	v_pk_mul_f32 v[138:139], v[176:177], v[182:183]
	v_pk_fma_f32 v[140:141], v[24:25], v[174:175], s[2:3]
	v_mov_b32_e32 v168, v185
	v_mov_b32_e32 v139, v141
	v_mov_b32_e32 v169, v187
	v_pk_mul_f32 v[142:143], v[194:195], v[138:139]
	v_pk_mul_f32 v[240:241], v[166:167], v[220:221]
	v_pk_mul_f32 v[242:243], v[168:169], v[222:223]
	ds_write_b128 v161, v[240:243] offset:24576
	v_pk_fma_f32 v[136:137], v[186:187], v[180:181], v[136:137] op_sel_hi:[1,0,1]
	v_xor_b32_e32 v166, 0x80000000, v138
	v_mul_f32_e32 v138, v143, v162
	v_fmac_f32_e32 v200, v40, v138
	v_pk_fma_f32 v[138:139], v[142:143], v[162:163], v[136:137] op_sel_hi:[1,0,1]
	v_pk_mul_f32 v[140:141], v[204:205], v[182:183]
	v_pk_fma_f32 v[136:137], v[32:33], v[202:203], s[2:3]
	v_xor_b32_e32 v167, 0x80000000, v140
	v_mov_b32_e32 v141, v137
	v_pk_mul_f32 v[136:137], v[170:171], v[140:141]
	v_mul_f32_e64 v168, v178, -v182
	v_mul_f32_e32 v140, v137, v163
	v_fmac_f32_e32 v200, v41, v140
	v_add_f32_e32 v140, -1.0, v146
	v_fma_f32 v141, v34, v140, 1.0
	v_mov_b32_e32 v144, v146
	v_xor_b32_e32 v140, 0x80000000, v168
	v_pk_fma_f32 v[138:139], v[136:137], v[162:163], v[138:139] op_sel:[0,1,0]
	v_pk_mul_f32 v[144:145], v[144:145], v[140:141]
	s_nop 0
	v_mul_f32_e32 v140, v145, v164
	v_pk_fma_f32 v[162:163], v[144:145], v[164:165], v[138:139] op_sel_hi:[1,0,1]
	v_add_f32_e32 v138, -1.0, v147
	v_mul_f32_e64 v164, v179, -v182
	v_fma_f32 v139, v35, v138, 1.0
	v_xor_b32_e32 v138, 0x80000000, v164
	v_pk_mul_f32 v[146:147], v[172:173], v[138:139]
	v_fmac_f32_e32 v200, v42, v140
	v_mov_b32_e32 v138, v142
	v_mov_b32_e32 v139, v136
	v_mov_b32_e32 v140, v144
	v_mov_b32_e32 v141, v146
	v_pk_mul_f32 v[244:245], v[138:139], v[224:225]
	v_pk_mul_f32 v[246:247], v[140:141], v[226:227]
	ds_write_b128 v161, v[244:247] offset:16400
	v_mov_b32_e32 v136, v143
	v_mov_b32_e32 v138, v145
	v_mov_b32_e32 v139, v147
	v_pk_mul_f32 v[248:249], v[136:137], v[224:225]
	v_pk_mul_f32 v[250:251], v[138:139], v[226:227]
	ds_write_b128 v161, v[248:251] offset:24592
	v_mov_b32_e32 v136, v165
	v_mul_f32_e32 v137, v147, v165
	v_fmac_f32_e32 v200, v43, v137
	v_pk_fma_f32 v[144:145], v[146:147], v[136:137], v[162:163] op_sel_hi:[1,0,1]
	v_mul_f32_e32 v228, v181, v228
	v_mul_f32_e32 v229, v201, v229
	v_cvt_pk_bf16_f32 v136, v228, v229
	v_mul_f32_e32 v230, v188, v230
	v_mul_f32_e32 v231, v189, v231
	v_cvt_pk_bf16_f32 v137, v230, v231
	v_mul_f32_e32 v232, v166, v232
	v_mul_f32_e32 v233, v167, v233
	v_cvt_pk_bf16_f32 v138, v232, v233
	v_mul_f32_e32 v234, v168, v234
	v_mul_f32_e32 v235, v164, v235
	v_cvt_pk_bf16_f32 v139, v234, v235
	v_cvt_pk_bf16_f32 v140, v206, v207
	v_cvt_pk_bf16_f32 v141, v208, v209
	v_cvt_pk_bf16_f32 v142, v210, v211
	v_cvt_pk_bf16_f32 v143, v212, v213
	ds_write_b128 v214, v[136:139] offset:8192
	ds_write_b128 v214, v[140:143] offset:12288
	v_add_f32_dpp v136, v200, v200 quad_perm:[1,0,3,2] row_mask:0xf bank_mask:0xf bound_ctrl:1
	v_mov_b32_dpp v137, v145 quad_perm:[1,0,3,2] row_mask:0xf bank_mask:0xf bound_ctrl:1
	s_nop 0
	v_add_f32_dpp v136, v136, v136 quad_perm:[2,3,0,1] row_mask:0xf bank_mask:0xf bound_ctrl:1
	s_nop 1
	v_add_f32_dpp v140, v136, v136 row_half_mirror row_mask:0xf bank_mask:0xf bound_ctrl:1
	v_mov_b32_dpp v136, v144 quad_perm:[1,0,3,2] row_mask:0xf bank_mask:0xf bound_ctrl:1
	v_pk_add_f32 v[136:137], v[144:145], v[136:137]
	ds_write_b32 v215, v140 offset:57216
	s_nop 0
	v_mov_b32_dpp v138, v136 quad_perm:[2,3,0,1] row_mask:0xf bank_mask:0xf bound_ctrl:1
	v_mov_b32_dpp v139, v137 quad_perm:[2,3,0,1] row_mask:0xf bank_mask:0xf bound_ctrl:1
	v_pk_add_f32 v[136:137], v[136:137], v[138:139]
	s_nop 1
	v_mov_b32_dpp v138, v136 row_half_mirror row_mask:0xf bank_mask:0xf bound_ctrl:1
	v_mov_b32_dpp v139, v137 row_half_mirror row_mask:0xf bank_mask:0xf bound_ctrl:1
	v_pk_add_f32 v[136:137], v[136:137], v[138:139]
	ds_write_b64 v216, v[136:137] offset:57216
	v_mul_f32_dpp v220, v236, v228 row_shr:8 row_mask:0xf bank_mask:0xf bound_ctrl:1
	v_mul_f32_dpp v221, v240, v228 row_shr:8 row_mask:0xf bank_mask:0xf bound_ctrl:1
	v_mul_f32_dpp v222, v236, v206 row_shr:8 row_mask:0xf bank_mask:0xf bound_ctrl:1
	v_mul_f32_dpp v223, v240, v206 row_shr:8 row_mask:0xf bank_mask:0xf bound_ctrl:1
	v_fmac_f32_dpp v220, v237, v229 row_shr:8 row_mask:0xf bank_mask:0xf bound_ctrl:1
	v_fmac_f32_dpp v221, v241, v229 row_shr:8 row_mask:0xf bank_mask:0xf bound_ctrl:1
	v_fmac_f32_dpp v222, v237, v207 row_shr:8 row_mask:0xf bank_mask:0xf bound_ctrl:1
	v_fmac_f32_dpp v223, v241, v207 row_shr:8 row_mask:0xf bank_mask:0xf bound_ctrl:1
	v_fmac_f32_dpp v220, v238, v230 row_shr:8 row_mask:0xf bank_mask:0xf bound_ctrl:1
	v_fmac_f32_dpp v221, v242, v230 row_shr:8 row_mask:0xf bank_mask:0xf bound_ctrl:1
	v_fmac_f32_dpp v222, v238, v208 row_shr:8 row_mask:0xf bank_mask:0xf bound_ctrl:1
	v_fmac_f32_dpp v223, v242, v208 row_shr:8 row_mask:0xf bank_mask:0xf bound_ctrl:1
	v_fmac_f32_dpp v220, v239, v231 row_shr:8 row_mask:0xf bank_mask:0xf bound_ctrl:1
	v_fmac_f32_dpp v221, v243, v231 row_shr:8 row_mask:0xf bank_mask:0xf bound_ctrl:1
	v_fmac_f32_dpp v222, v239, v209 row_shr:8 row_mask:0xf bank_mask:0xf bound_ctrl:1
	v_fmac_f32_dpp v223, v243, v209 row_shr:8 row_mask:0xf bank_mask:0xf bound_ctrl:1
	v_fmac_f32_dpp v220, v244, v232 row_shr:8 row_mask:0xf bank_mask:0xf bound_ctrl:1
	v_fmac_f32_dpp v221, v248, v232 row_shr:8 row_mask:0xf bank_mask:0xf bound_ctrl:1
	v_fmac_f32_dpp v222, v244, v210 row_shr:8 row_mask:0xf bank_mask:0xf bound_ctrl:1
	v_fmac_f32_dpp v223, v248, v210 row_shr:8 row_mask:0xf bank_mask:0xf bound_ctrl:1
	v_fmac_f32_dpp v220, v245, v233 row_shr:8 row_mask:0xf bank_mask:0xf bound_ctrl:1
	v_fmac_f32_dpp v221, v249, v233 row_shr:8 row_mask:0xf bank_mask:0xf bound_ctrl:1
	v_fmac_f32_dpp v222, v245, v211 row_shr:8 row_mask:0xf bank_mask:0xf bound_ctrl:1
	v_fmac_f32_dpp v223, v249, v211 row_shr:8 row_mask:0xf bank_mask:0xf bound_ctrl:1
	v_fmac_f32_dpp v220, v246, v234 row_shr:8 row_mask:0xf bank_mask:0xf bound_ctrl:1
	v_fmac_f32_dpp v221, v250, v234 row_shr:8 row_mask:0xf bank_mask:0xf bound_ctrl:1
	v_fmac_f32_dpp v222, v246, v212 row_shr:8 row_mask:0xf bank_mask:0xf bound_ctrl:1
	v_fmac_f32_dpp v223, v250, v212 row_shr:8 row_mask:0xf bank_mask:0xf bound_ctrl:1
	v_fmac_f32_dpp v220, v247, v235 row_shr:8 row_mask:0xf bank_mask:0xf bound_ctrl:1
	v_fmac_f32_dpp v221, v251, v235 row_shr:8 row_mask:0xf bank_mask:0xf bound_ctrl:1
	v_fmac_f32_dpp v222, v247, v213 row_shr:8 row_mask:0xf bank_mask:0xf bound_ctrl:1
	v_fmac_f32_dpp v223, v251, v213 row_shr:8 row_mask:0xf bank_mask:0xf bound_ctrl:1
	v_add_f32_dpp v220, v220, v220 quad_perm:[1,0,3,2] row_mask:0xf bank_mask:0xf bound_ctrl:1
	v_add_f32_dpp v221, v221, v221 quad_perm:[1,0,3,2] row_mask:0xf bank_mask:0xf bound_ctrl:1
	v_add_f32_dpp v222, v222, v222 quad_perm:[1,0,3,2] row_mask:0xf bank_mask:0xf bound_ctrl:1
	v_add_f32_dpp v223, v223, v223 quad_perm:[1,0,3,2] row_mask:0xf bank_mask:0xf bound_ctrl:1
	v_add_f32_dpp v220, v220, v220 quad_perm:[2,3,0,1] row_mask:0xf bank_mask:0xf bound_ctrl:1
	v_add_f32_dpp v221, v221, v221 quad_perm:[2,3,0,1] row_mask:0xf bank_mask:0xf bound_ctrl:1
	v_add_f32_dpp v222, v222, v222 quad_perm:[2,3,0,1] row_mask:0xf bank_mask:0xf bound_ctrl:1
	v_add_f32_dpp v223, v223, v223 quad_perm:[2,3,0,1] row_mask:0xf bank_mask:0xf bound_ctrl:1
	v_add_f32_dpp v220, v220, v220 row_half_mirror row_mask:0xf bank_mask:0xf bound_ctrl:1
	v_add_f32_dpp v221, v221, v221 row_half_mirror row_mask:0xf bank_mask:0xf bound_ctrl:1
	v_add_f32_dpp v222, v222, v222 row_half_mirror row_mask:0xf bank_mask:0xf bound_ctrl:1
	v_add_f32_dpp v223, v223, v223 row_half_mirror row_mask:0xf bank_mask:0xf bound_ctrl:1
	v_cmp_lt_u32_e32 vcc, 0x7530, v161
	v_lshrrev_b32_e32 v217, 7, v154
	v_lshlrev_b32_e32 v217, 4, v217
	v_not_b32_e32 v254, v219
	v_and_b32_e32 v254, 8, v254
	v_lshlrev_b32_e32 v254, 7, v254
	v_mov_b32_e32 v224, 0x100
	v_cndmask_b32_e32 v224, 0, v224, vcc
	v_add3_u32 v217, v217, v254, v224
	v_add_u32_e32 v217, 0x24010, v217
	ds_write_b128 v217, v[220:223]
	s_waitcnt vmcnt(0)
	s_cbranch_scc1 .LBB0_784
	v_lshl_add_u64 v[84:85], v[128:129], 0, s[4:5]
	v_add_co_u32_e32 v72, vcc, 0x239a5000, v84
	v_lshl_add_u64 v[92:93], v[130:131], 0, s[4:5]
	s_nop 0
	v_addc_co_u32_e32 v73, vcc, 0, v85, vcc
	v_add_co_u32_e32 v74, vcc, 0x239a3000, v84
	v_lshl_add_u64 v[80:81], v[132:133], 0, s[4:5]
	s_nop 0
	v_addc_co_u32_e32 v75, vcc, 0, v85, vcc
	v_add_co_u32_e32 v88, vcc, 0x239a4000, v84
	v_lshl_add_u64 v[86:87], v[134:135], 0, s[4:5]
	s_nop 0
	v_addc_co_u32_e32 v89, vcc, 0, v85, vcc
	v_add_co_u32_e32 v96, vcc, 0x239a6000, v92
	global_load_dwordx4 v[68:71], v[72:73], off
	global_load_dwordx4 v[76:79], v[72:73], off offset:2048
	v_addc_co_u32_e32 v97, vcc, 0, v93, vcc
	v_add_co_u32_e32 v104, vcc, 0x239a4000, v92
	global_load_dwordx4 v[72:75], v[74:75], off offset:1792
	s_nop 0
	global_load_dwordx4 v[80:83], v[80:81], off
	v_addc_co_u32_e32 v105, vcc, 0, v93, vcc
	global_load_dwordx4 v[84:87], v[86:87], off
	s_nop 0
	global_load_dwordx4 v[88:91], v[88:89], off offset:1792
	s_nop 0
	global_load_dwordx4 v[92:95], v[96:97], off offset:2048
	global_load_dwordx4 v[100:103], v[96:97], off offset:2176
	s_nop 0
	global_load_dwordx4 v[96:99], v[104:105], off offset:3840
	s_nop 0
	global_load_dwordx4 v[104:107], v[104:105], off offset:3968
	s_branch .LBB0_784

; DI void scan_item(const Params& p, char* smem, int b, int h, bool prompt, const int g_wave) {
;     ...
;     const int li = lane & 15, g = lane >> 4, irow = wid * 16 + li;
;     f32x2 S0[4], S1[4];
;     if (prompt) { for (int e = 0; e < 4; ++e) { S0[e] = (f32x2){0.f, 0.f}; S1[e] = (f32x2){0.f, 0.f}; } }
;     else {
;       const float* s0 = p.state_wkv + ((size_t)(b * 16 + h) * 64 + irow) * 64 + 8 * g;
;       for (int e = 0; e < 4; ++e) { S0[e] = (f32x2){s0[2 * e], s0[2 * e + 1]}; S1[e] = (f32x2){s0[32 + 2 * e], s0[32 + 2 * e + 1]}; }
;     }
;     const int abf_off = ((lane & 3) == 1 ? 12288 : 8192) + 16 * g;
;     __syncthreads();
.LBB0_794:
	v_and_b32_e32 v21, 3, v119
	v_mov_b32_e32 v22, 0x2000
	v_mov_b32_e32 v23, 0x3000
	v_cmp_eq_u32_e32 vcc, 1, v21
	v_lshlrev_b32_e32 v83, 2, v21
	v_lshrrev_b32_e32 v21, 1, v82
	v_cndmask_b32_e32 v77, v22, v23, vcc
	v_add_u32_e32 v77, v77, v21
	v_mov_b32_e32 v22, 0x4000
	v_add3_u32 v83, v83, v82, v22
	v_add_u32_e32 v27, 0x2000, v83
	v_lshlrev_b32_e32 v84, 2, v79
	v_add_u32_e32 v84, 0xa000, v84
	v_mov_b32_e32 v85, v82
	v_and_b32_e32 v21, 16, v119
	v_lshlrev_b32_e32 v24, 9, v21
	v_and_b32_e32 v21, 32, v119
	v_lshl_add_u32 v24, v21, 3, v24
	v_lshl_add_u32 v24, v20, 2, v24
	v_add_u32_e32 v24, 0x4000, v24
	v_and_b32_e32 v21, 1, v119
	v_lshlrev_b32_e32 v25, 12, v21
	v_and_b32_e32 v21, 2, v119
	v_lshl_add_u32 v25, v21, 6, v25
	v_lshrrev_b32_e32 v21, 1, v82
	v_add_u32_e32 v25, v25, v21
	v_add_u32_e32 v25, 0x2000, v25
	v_and_b32_e32 v21, 16, v119
	v_cmp_ne_u32_e64 s[34:35], 0, v21
	v_and_b32_e32 v21, 32, v119
	v_cmp_ne_u32_e64 s[44:45], 0, v21
	s_mov_b32 s0, 0
	s_waitcnt vmcnt(0)
	s_barrier

; DI void scan_item(const Params& p, char* smem, int b, int h, bool prompt, const int g_wave) {
;     ...
;       f32x4v Pw0, Pw1, Pw2, Pw3, Pb0, Pb1, Pb2, Pb3, Pk0, Pk1, Pk2, Pk3; bf16x8 Pa0, Pa1; float Pv; float2 Ps;
;       f32x4v Qw0, Qw1, Qw2, Qw3, Qb0, Qb1, Qb2, Qb3, Qk0, Qk1, Qk2, Qk3; bf16x8 Qa0, Qa1; float Qv; float2 Qs;
;       LOADV(P, 0);
; #pragma unroll 1
;       for (int t = 0; t < 32; t += 2) {
;         LOADV(Q, t + 1);
;         STEP(P, t);
;         LOADV(P, t + 2);
;         STEP(Q, t + 1);
;       }
.Lsc_newfmt:
	s_add_i32 s1, s1, 0xffff1f80
	v_add_u32_e32 v86, s1, v24
	v_add_u32_e32 v89, s1, v25
	s_lshl_b32 s1, s0, 8
	s_and_b32 s1, s1, 0x100
	s_add_i32 s1, s1, 0x24010
	v_mov_b32_e32 v26, s1
	ds_read_b64 v[72:73], v89
	ds_read_b64 v[74:75], v89 offset:32
	ds_read_b64 v[68:69], v89 offset:64
	ds_read_b64 v[70:71], v89 offset:96
	ds_read_b32 v60, v86
	ds_read_b32 v61, v86 offset:64
	ds_read_b32 v62, v86 offset:128
	ds_read_b32 v63, v86 offset:192
	ds_read2st64_b32 v[64:65], v87 offset0:0 offset1:1
	ds_read_b128 v[120:123], v111
	ds_read_b128 v[124:127], v26
	s_mov_b32 s4, -4
.Lsc_loopC:
	ds_read_b128 v[52:55], v88 offset:768
	ds_read_b128 v[40:43], v88 offset:832
	ds_read_b128 v[28:31], v88 offset:896
	ds_read_b128 v[20:23], v88 offset:960
	ds_read_b64 v[138:139], v89 offset:256
	ds_read_b64 v[140:141], v89 offset:288
	ds_read_b64 v[142:143], v89 offset:320
	ds_read_b64 v[144:145], v89 offset:352
	ds_read_b32 v106, v86 offset:512
	ds_read_b32 v107, v86 offset:576
	ds_read_b32 v108, v86 offset:640
	ds_read_b32 v109, v86 offset:704
	ds_read2st64_b32 v[66:67], v87 offset0:2 offset1:3
	ds_read_b128 v[128:131], v111 offset:16
	ds_read_b128 v[132:135], v26 offset:16
	v_cvt_pk_bf16_f32 v146, v16, v17
	v_cvt_pk_bf16_f32 v147, v18, v19
	v_cvt_pk_bf16_f32 v148, v12, v13
	v_cvt_pk_bf16_f32 v149, v14, v15
	v_cvt_pk_bf16_f32 v150, v4, v5
	v_cvt_pk_bf16_f32 v151, v6, v7
	v_cvt_pk_bf16_f32 v152, v8, v9
	v_cvt_pk_bf16_f32 v153, v10, v11
	s_waitcnt lgkmcnt(11)
	v_mfma_f32_16x16x32_bf16 v[72:75], v[72:75], v[146:149], 0
	v_mfma_f32_16x16x32_bf16 v[68:71], v[68:71], v[150:153], v[72:75]
	s_nop 7
	v_fma_f32 v160, v68, v124, v70
	v_fma_f32 v161, v68, v126, v71
	v_fma_f32 v158, v68, v120, v69
	v_fmac_f32_e32 v160, v64, v125
	v_fmac_f32_e32 v161, v64, v127
	v_fmac_f32_e32 v158, v64, v121
	v_cndmask_b32_e64 v136, v68, v64, s[34:35]
	v_fmac_f32_e32 v161, v160, v122
	v_cndmask_b32_e64 v137, v160, v65, s[34:35]
	v_fmac_f32_e32 v161, v65, v123
	v_cndmask_b32_e64 v136, v136, v137, s[44:45]
	ds_write_b32 v87, v158 offset:8192
	ds_write_b32 v87, v161 offset:8448
	v_mfma_f32_16x16x4_f32 v[16:19], v60, v136, v[16:19]
	v_mfma_f32_16x16x4_f32 v[12:15], v61, v136, v[12:15]
	v_mfma_f32_16x16x4_f32 v[4:7], v62, v136, v[4:7]
	v_mfma_f32_16x16x4_f32 v[8:11], v63, v136, v[8:11]
	v_add_u32_e32 v88, 0x400, v88
	v_add_u32_e32 v86, 0x400, v86
	v_add_u32_e32 v89, 0x200, v89
	v_add_u32_e32 v87, 0x400, v87
	v_add_u32_e32 v111, 32, v111
	v_add_u32_e32 v26, 32, v26
	s_nop 0
	ds_read_b64 v[72:73], v89
	ds_read_b64 v[74:75], v89 offset:32
	ds_read_b64 v[68:69], v89 offset:64
	ds_read_b64 v[70:71], v89 offset:96
	ds_read_b32 v60, v86
	ds_read_b32 v61, v86 offset:64
	ds_read_b32 v62, v86 offset:128
	ds_read_b32 v63, v86 offset:192
	ds_read2st64_b32 v[64:65], v87 offset0:0 offset1:1
	ds_read_b128 v[120:123], v111
	ds_read_b128 v[124:127], v26
	v_cvt_pk_bf16_f32 v146, v16, v17
	v_cvt_pk_bf16_f32 v147, v18, v19
	v_cvt_pk_bf16_f32 v148, v12, v13
	v_cvt_pk_bf16_f32 v149, v14, v15
	v_cvt_pk_bf16_f32 v150, v4, v5
	v_cvt_pk_bf16_f32 v151, v6, v7
	v_cvt_pk_bf16_f32 v152, v8, v9
	v_cvt_pk_bf16_f32 v153, v10, v11
	s_waitcnt lgkmcnt(11)
	v_mfma_f32_16x16x32_bf16 v[138:141], v[138:141], v[146:149], 0
	v_mfma_f32_16x16x32_bf16 v[142:145], v[142:145], v[150:153], v[138:141]
	s_nop 7
	v_fma_f32 v160, v142, v132, v144
	v_fma_f32 v161, v142, v134, v145
	v_fma_f32 v158, v142, v128, v143
	v_fmac_f32_e32 v160, v66, v133
	v_fmac_f32_e32 v161, v66, v135
	v_fmac_f32_e32 v158, v66, v129
	v_cndmask_b32_e64 v136, v142, v66, s[34:35]
	v_fmac_f32_e32 v161, v160, v130
	v_cndmask_b32_e64 v137, v160, v67, s[34:35]
	v_fmac_f32_e32 v161, v67, v131
	v_cndmask_b32_e64 v136, v136, v137, s[44:45]
	ds_write_b32 v87, v158 offset:7680
	ds_write_b32 v87, v161 offset:7936
	v_mfma_f32_16x16x4_f32 v[16:19], v106, v136, v[16:19]
	v_mfma_f32_16x16x4_f32 v[12:15], v107, v136, v[12:15]
	v_mfma_f32_16x16x4_f32 v[4:7], v108, v136, v[4:7]
	v_mfma_f32_16x16x4_f32 v[8:11], v109, v136, v[8:11]
	s_add_i32 s4, s4, 4
	s_cmp_gt_u32 s4, 27
	s_nop 5
	v_pk_mul_f32 v[16:17], v[16:17], v[52:53]
	v_pk_mul_f32 v[18:19], v[18:19], v[54:55]
	v_pk_mul_f32 v[12:13], v[12:13], v[40:41]
	v_pk_mul_f32 v[14:15], v[14:15], v[42:43]
	v_pk_mul_f32 v[4:5], v[4:5], v[28:29]
	v_pk_mul_f32 v[6:7], v[6:7], v[30:31]
	v_pk_mul_f32 v[8:9], v[8:9], v[20:21]
	v_pk_mul_f32 v[10:11], v[10:11], v[22:23]
	s_cbranch_scc0 .Lsc_loopC
